# GEMM main loops: snake order of the 8 MFMAs per k-group so consecutive MFMAs share one A/B operand (less operand toggling)
# speedup vs baseline: 1.0013x; 1.0013x over previous
.LBB0_120:
	s_add_u32 s28, s40, 0xfff80080
	s_addc_u32 s29, s41, -1
	s_add_i32 s54, 0, 0x10000
	s_cmp_eq_u32 s53, 28
	s_cselect_b32 s29, s23, s29
	s_cselect_b32 s28, s22, s28
	s_cselect_b32 s43, s21, s52
	s_cselect_b32 s42, s50, s51
	s_add_i32 s56, 0, 0x14000
	v_add_u32_e32 v142, s54, v212
	v_add_u32_e32 v158, s56, v212
	ds_read_b128 v[130:133], v142
	ds_read_b128 v[134:137], v142 offset:1024
	ds_read_b128 v[138:141], v142 offset:2048
	ds_read_b128 v[142:145], v142 offset:3072
	ds_read_b128 v[146:149], v158
	ds_read_b128 v[150:153], v158 offset:1024
	ds_read_b128 v[154:157], v158 offset:2048
	ds_read_b128 v[158:161], v158 offset:3072
	v_lshl_add_u64 v[204:205], s[40:41], 0, v[184:185]
	s_add_i32 m0, s24, 0xc000
	ds_read_b128 v[162:165], v213
	ds_read_b128 v[166:169], v213 offset:1024
	ds_read_b128 v[170:173], v213 offset:2048
	ds_read_b128 v[174:177], v213 offset:3072
	ds_read_b128 v[188:191], v213 offset:4096
	ds_read_b128 v[192:195], v213 offset:5120
	ds_read_b128 v[196:199], v213 offset:6144
	ds_read_b128 v[200:203], v213 offset:7168
	global_load_lds_dwordx4 v[204:205], off
	v_lshl_add_u64 v[204:205], s[40:41], 0, v[186:187]
	s_add_i32 m0, s24, 0xe000
	s_nop 0
	global_load_lds_dwordx4 v[204:205], off
	s_waitcnt vmcnt(8)
	s_waitcnt lgkmcnt(0)
	s_barrier
	s_setprio 1
	s_waitcnt lgkmcnt(0)
	v_mfma_f32_16x16x32_bf16 v[126:129], v[130:133], v[162:165], v[126:129]
	v_mfma_f32_16x16x32_bf16 v[122:125], v[138:141], v[162:165], v[122:125]
	v_mfma_f32_16x16x32_bf16 v[106:109], v[138:141], v[170:173], v[106:109]
	v_mfma_f32_16x16x32_bf16 v[110:113], v[130:133], v[170:173], v[110:113]
	v_mfma_f32_16x16x32_bf16 v[94:97], v[130:133], v[188:191], v[94:97]
	v_mfma_f32_16x16x32_bf16 v[90:93], v[138:141], v[188:191], v[90:93]
	v_mfma_f32_16x16x32_bf16 v[74:77], v[138:141], v[196:199], v[74:77]
	v_mfma_f32_16x16x32_bf16 v[78:81], v[130:133], v[196:199], v[78:81]
	v_mfma_f32_16x16x32_bf16 v[126:129], v[134:137], v[166:169], v[126:129]
	v_mfma_f32_16x16x32_bf16 v[122:125], v[142:145], v[166:169], v[122:125]
	v_mfma_f32_16x16x32_bf16 v[106:109], v[142:145], v[174:177], v[106:109]
	v_mfma_f32_16x16x32_bf16 v[110:113], v[134:137], v[174:177], v[110:113]
	v_mfma_f32_16x16x32_bf16 v[94:97], v[134:137], v[192:195], v[94:97]
	v_mfma_f32_16x16x32_bf16 v[90:93], v[142:145], v[192:195], v[90:93]
	v_mfma_f32_16x16x32_bf16 v[74:77], v[142:145], v[200:203], v[74:77]
	v_mfma_f32_16x16x32_bf16 v[78:81], v[134:137], v[200:203], v[78:81]
	s_setprio 0
	s_setprio 1
	v_mfma_f32_16x16x32_bf16 v[118:121], v[146:149], v[162:165], v[118:121]
	v_mfma_f32_16x16x32_bf16 v[114:117], v[154:157], v[162:165], v[114:117]
	v_mfma_f32_16x16x32_bf16 v[98:101], v[154:157], v[170:173], v[98:101]
	v_mfma_f32_16x16x32_bf16 v[102:105], v[146:149], v[170:173], v[102:105]
	v_mfma_f32_16x16x32_bf16 v[86:89], v[146:149], v[188:191], v[86:89]
	v_mfma_f32_16x16x32_bf16 v[82:85], v[154:157], v[188:191], v[82:85]
	v_mfma_f32_16x16x32_bf16 v[66:69], v[154:157], v[196:199], v[66:69]
	v_mfma_f32_16x16x32_bf16 v[70:73], v[146:149], v[196:199], v[70:73]
	v_mfma_f32_16x16x32_bf16 v[118:121], v[150:153], v[166:169], v[118:121]
	v_mfma_f32_16x16x32_bf16 v[114:117], v[158:161], v[166:169], v[114:117]
	v_mfma_f32_16x16x32_bf16 v[98:101], v[158:161], v[174:177], v[98:101]
	v_mfma_f32_16x16x32_bf16 v[102:105], v[150:153], v[174:177], v[102:105]
	v_mfma_f32_16x16x32_bf16 v[86:89], v[150:153], v[192:195], v[86:89]
	v_mfma_f32_16x16x32_bf16 v[82:85], v[158:161], v[192:195], v[82:85]
	v_mfma_f32_16x16x32_bf16 v[66:69], v[158:161], v[200:203], v[66:69]
	v_mfma_f32_16x16x32_bf16 v[70:73], v[150:153], v[200:203], v[70:73]
	s_setprio 0
	s_barrier
	s_add_i32 s54, s54, s1
	v_lshl_add_u64 v[204:205], s[42:43], 0, v[32:33]
	s_mov_b32 m0, s54
	ds_read_b128 v[162:165], v213 offset:16384
	ds_read_b128 v[166:169], v213 offset:17408
	ds_read_b128 v[170:173], v213 offset:18432
	ds_read_b128 v[174:177], v213 offset:19456
	ds_read_b128 v[188:191], v213 offset:20480
	ds_read_b128 v[192:195], v213 offset:21504
	ds_read_b128 v[196:199], v213 offset:22528
	ds_read_b128 v[200:203], v213 offset:23552
	global_load_lds_dwordx4 v[204:205], off
	s_add_i32 m0, s54, 0x2000
	s_add_u32 s54, s42, 0x80000
	v_lshl_add_u64 v[206:207], s[42:43], 0, v[182:183]
	s_addc_u32 s55, s43, 0
	s_add_i32 s56, s56, s1
	global_load_lds_dwordx4 v[206:207], off
	v_lshl_add_u64 v[208:209], s[54:55], 0, v[32:33]
	s_mov_b32 m0, s56
	v_lshl_add_u64 v[214:215], s[28:29], 0, v[180:181]
	global_load_lds_dwordx4 v[208:209], off
	v_lshl_add_u64 v[208:209], s[54:55], 0, v[182:183]
	s_add_i32 m0, s56, 0x2000
	s_nop 0
	global_load_lds_dwordx4 v[208:209], off
	v_lshl_add_u64 v[208:209], s[28:29], 0, v[178:179]
	s_mov_b32 m0, s24
	s_nop 0
	global_load_lds_dwordx4 v[208:209], off
	s_mov_b32 m0, s25
	s_nop 0
	global_load_lds_dwordx4 v[214:215], off
	s_waitcnt vmcnt(8)
	s_waitcnt lgkmcnt(0)
	s_barrier
	s_setprio 1
	s_waitcnt lgkmcnt(0)
	v_mfma_f32_16x16x32_bf16 v[62:65], v[130:133], v[162:165], v[62:65]
	v_mfma_f32_16x16x32_bf16 v[58:61], v[138:141], v[162:165], v[58:61]
	v_mfma_f32_16x16x32_bf16 v[42:45], v[138:141], v[170:173], v[42:45]
	v_mfma_f32_16x16x32_bf16 v[46:49], v[130:133], v[170:173], v[46:49]
	v_mfma_f32_16x16x32_bf16 v[28:31], v[130:133], v[188:191], v[28:31]
	v_mfma_f32_16x16x32_bf16 v[24:27], v[138:141], v[188:191], v[24:27]
	v_mfma_f32_16x16x32_bf16 v[8:11], v[138:141], v[196:199], v[8:11]
	v_mfma_f32_16x16x32_bf16 v[12:15], v[130:133], v[196:199], v[12:15]
	v_mfma_f32_16x16x32_bf16 v[62:65], v[134:137], v[166:169], v[62:65]
	v_mfma_f32_16x16x32_bf16 v[58:61], v[142:145], v[166:169], v[58:61]
	v_mfma_f32_16x16x32_bf16 v[42:45], v[142:145], v[174:177], v[42:45]
	v_mfma_f32_16x16x32_bf16 v[46:49], v[134:137], v[174:177], v[46:49]
	v_mfma_f32_16x16x32_bf16 v[28:31], v[134:137], v[192:195], v[28:31]
	v_mfma_f32_16x16x32_bf16 v[24:27], v[142:145], v[192:195], v[24:27]
	v_mfma_f32_16x16x32_bf16 v[8:11], v[142:145], v[200:203], v[8:11]
	v_mfma_f32_16x16x32_bf16 v[12:15], v[134:137], v[200:203], v[12:15]
	s_setprio 0
	s_setprio 1
	v_mfma_f32_16x16x32_bf16 v[54:57], v[146:149], v[162:165], v[54:57]
	v_mfma_f32_16x16x32_bf16 v[50:53], v[154:157], v[162:165], v[50:53]
	v_mfma_f32_16x16x32_bf16 v[34:37], v[154:157], v[170:173], v[34:37]
	v_mfma_f32_16x16x32_bf16 v[38:41], v[146:149], v[170:173], v[38:41]
	v_mfma_f32_16x16x32_bf16 v[20:23], v[146:149], v[188:191], v[20:23]
	v_mfma_f32_16x16x32_bf16 v[16:19], v[154:157], v[188:191], v[16:19]
	v_mfma_f32_16x16x32_bf16 v[0:3], v[154:157], v[196:199], v[0:3]
	v_mfma_f32_16x16x32_bf16 v[4:7], v[146:149], v[196:199], v[4:7]
	v_mfma_f32_16x16x32_bf16 v[54:57], v[150:153], v[166:169], v[54:57]
	v_mfma_f32_16x16x32_bf16 v[50:53], v[158:161], v[166:169], v[50:53]
	v_mfma_f32_16x16x32_bf16 v[34:37], v[158:161], v[174:177], v[34:37]
	v_mfma_f32_16x16x32_bf16 v[38:41], v[150:153], v[174:177], v[38:41]
	v_mfma_f32_16x16x32_bf16 v[20:23], v[150:153], v[192:195], v[20:23]
	v_mfma_f32_16x16x32_bf16 v[16:19], v[158:161], v[192:195], v[16:19]
	v_mfma_f32_16x16x32_bf16 v[0:3], v[158:161], v[200:203], v[0:3]
	v_mfma_f32_16x16x32_bf16 v[4:7], v[150:153], v[200:203], v[4:7]
	s_setprio 0
	s_barrier
	s_add_i32 s54, 0, 0x18000
	s_add_i32 s55, 0, 0x1c000
	v_add_u32_e32 v142, s54, v212
	v_add_u32_e32 v158, s55, v212
	ds_read_b128 v[130:133], v142
	ds_read_b128 v[134:137], v142 offset:1024
	ds_read_b128 v[138:141], v142 offset:2048
	ds_read_b128 v[142:145], v142 offset:3072
	ds_read_b128 v[146:149], v158
	ds_read_b128 v[150:153], v158 offset:1024
	ds_read_b128 v[154:157], v158 offset:2048
	ds_read_b128 v[158:161], v158 offset:3072
	s_add_u32 s28, s28, 0x80000
	s_addc_u32 s29, s29, 0
	s_mov_b32 m0, s33
	v_lshl_add_u64 v[216:217], s[28:29], 0, v[178:179]
	ds_read_b128 v[162:165], v213 offset:32768
	ds_read_b128 v[166:169], v213 offset:33792
	ds_read_b128 v[170:173], v213 offset:34816
	ds_read_b128 v[174:177], v213 offset:35840
	ds_read_b128 v[188:191], v213 offset:36864
	ds_read_b128 v[192:195], v213 offset:37888
	ds_read_b128 v[196:199], v213 offset:38912
	ds_read_b128 v[200:203], v213 offset:39936
	global_load_lds_dwordx4 v[216:217], off
	v_lshl_add_u64 v[216:217], s[28:29], 0, v[180:181]
	s_mov_b32 m0, s36
	s_nop 0
	global_load_lds_dwordx4 v[216:217], off
	s_waitcnt vmcnt(8)
	s_waitcnt lgkmcnt(0)
	s_barrier
	s_setprio 1
	s_waitcnt lgkmcnt(0)
	v_mfma_f32_16x16x32_bf16 v[126:129], v[130:133], v[162:165], v[126:129]
	v_mfma_f32_16x16x32_bf16 v[122:125], v[138:141], v[162:165], v[122:125]
	v_mfma_f32_16x16x32_bf16 v[106:109], v[138:141], v[170:173], v[106:109]
	v_mfma_f32_16x16x32_bf16 v[110:113], v[130:133], v[170:173], v[110:113]
	v_mfma_f32_16x16x32_bf16 v[94:97], v[130:133], v[188:191], v[94:97]
	v_mfma_f32_16x16x32_bf16 v[90:93], v[138:141], v[188:191], v[90:93]
	v_mfma_f32_16x16x32_bf16 v[74:77], v[138:141], v[196:199], v[74:77]
	v_mfma_f32_16x16x32_bf16 v[78:81], v[130:133], v[196:199], v[78:81]
	v_mfma_f32_16x16x32_bf16 v[126:129], v[134:137], v[166:169], v[126:129]
	v_mfma_f32_16x16x32_bf16 v[122:125], v[142:145], v[166:169], v[122:125]
	v_mfma_f32_16x16x32_bf16 v[106:109], v[142:145], v[174:177], v[106:109]
	v_mfma_f32_16x16x32_bf16 v[110:113], v[134:137], v[174:177], v[110:113]
	v_mfma_f32_16x16x32_bf16 v[94:97], v[134:137], v[192:195], v[94:97]
	v_mfma_f32_16x16x32_bf16 v[90:93], v[142:145], v[192:195], v[90:93]
	v_mfma_f32_16x16x32_bf16 v[74:77], v[142:145], v[200:203], v[74:77]
	v_mfma_f32_16x16x32_bf16 v[78:81], v[134:137], v[200:203], v[78:81]
	s_setprio 0
	s_setprio 1
	v_mfma_f32_16x16x32_bf16 v[118:121], v[146:149], v[162:165], v[118:121]
	v_mfma_f32_16x16x32_bf16 v[114:117], v[154:157], v[162:165], v[114:117]
	v_mfma_f32_16x16x32_bf16 v[98:101], v[154:157], v[170:173], v[98:101]
	v_mfma_f32_16x16x32_bf16 v[102:105], v[146:149], v[170:173], v[102:105]
	v_mfma_f32_16x16x32_bf16 v[86:89], v[146:149], v[188:191], v[86:89]
	v_mfma_f32_16x16x32_bf16 v[82:85], v[154:157], v[188:191], v[82:85]
	v_mfma_f32_16x16x32_bf16 v[66:69], v[154:157], v[196:199], v[66:69]
	v_mfma_f32_16x16x32_bf16 v[70:73], v[146:149], v[196:199], v[70:73]
	v_mfma_f32_16x16x32_bf16 v[118:121], v[150:153], v[166:169], v[118:121]
	v_mfma_f32_16x16x32_bf16 v[114:117], v[158:161], v[166:169], v[114:117]
	v_mfma_f32_16x16x32_bf16 v[98:101], v[158:161], v[174:177], v[98:101]
	v_mfma_f32_16x16x32_bf16 v[102:105], v[150:153], v[174:177], v[102:105]
	v_mfma_f32_16x16x32_bf16 v[86:89], v[150:153], v[192:195], v[86:89]
	v_mfma_f32_16x16x32_bf16 v[82:85], v[158:161], v[192:195], v[82:85]
	v_mfma_f32_16x16x32_bf16 v[66:69], v[158:161], v[200:203], v[66:69]
	v_mfma_f32_16x16x32_bf16 v[70:73], v[150:153], v[200:203], v[70:73]
	s_setprio 0
	s_barrier
	s_add_i32 s28, s54, s1
	v_lshl_add_u64 v[204:205], v[204:205], 0, s[34:35]
	s_mov_b32 m0, s28
	ds_read_b128 v[162:165], v213 offset:49152
	ds_read_b128 v[166:169], v213 offset:50176
	ds_read_b128 v[170:173], v213 offset:51200
	ds_read_b128 v[174:177], v213 offset:52224
	ds_read_b128 v[188:191], v213 offset:53248
	ds_read_b128 v[192:195], v213 offset:54272
	ds_read_b128 v[196:199], v213 offset:55296
	ds_read_b128 v[200:203], v213 offset:56320
	global_load_lds_dwordx4 v[204:205], off
	s_add_i32 m0, s28, 0x2000
	s_add_u32 s28, s42, 0x80080
	v_lshl_add_u64 v[204:205], v[206:207], 0, s[34:35]
	s_addc_u32 s29, s43, 0
	s_add_i32 s42, s55, s1
	global_load_lds_dwordx4 v[204:205], off
	v_lshl_add_u64 v[204:205], s[28:29], 0, v[32:33]
	s_mov_b32 m0, s42
	s_nop 0
	global_load_lds_dwordx4 v[204:205], off
	v_lshl_add_u64 v[204:205], s[28:29], 0, v[182:183]
	s_add_i32 m0, s42, 0x2000
	s_nop 0
	global_load_lds_dwordx4 v[204:205], off
	v_lshl_add_u64 v[204:205], v[208:209], 0, s[34:35]
	s_mov_b32 m0, s44
	s_nop 0
	global_load_lds_dwordx4 v[204:205], off
	v_lshl_add_u64 v[204:205], v[214:215], 0, s[34:35]
	s_mov_b32 m0, s45
	s_nop 0
	global_load_lds_dwordx4 v[204:205], off
	s_waitcnt vmcnt(8)
	s_waitcnt lgkmcnt(0)
	s_barrier
	s_setprio 1
	s_waitcnt lgkmcnt(0)
	v_mfma_f32_16x16x32_bf16 v[62:65], v[130:133], v[162:165], v[62:65]
	v_mfma_f32_16x16x32_bf16 v[58:61], v[138:141], v[162:165], v[58:61]
	v_mfma_f32_16x16x32_bf16 v[42:45], v[138:141], v[170:173], v[42:45]
	v_mfma_f32_16x16x32_bf16 v[46:49], v[130:133], v[170:173], v[46:49]
	v_mfma_f32_16x16x32_bf16 v[28:31], v[130:133], v[188:191], v[28:31]
	v_mfma_f32_16x16x32_bf16 v[24:27], v[138:141], v[188:191], v[24:27]
	v_mfma_f32_16x16x32_bf16 v[8:11], v[138:141], v[196:199], v[8:11]
	v_mfma_f32_16x16x32_bf16 v[12:15], v[130:133], v[196:199], v[12:15]
	v_mfma_f32_16x16x32_bf16 v[62:65], v[134:137], v[166:169], v[62:65]
	v_mfma_f32_16x16x32_bf16 v[58:61], v[142:145], v[166:169], v[58:61]
	v_mfma_f32_16x16x32_bf16 v[42:45], v[142:145], v[174:177], v[42:45]
	v_mfma_f32_16x16x32_bf16 v[46:49], v[134:137], v[174:177], v[46:49]
	v_mfma_f32_16x16x32_bf16 v[28:31], v[134:137], v[192:195], v[28:31]
	v_mfma_f32_16x16x32_bf16 v[24:27], v[142:145], v[192:195], v[24:27]
	v_mfma_f32_16x16x32_bf16 v[8:11], v[142:145], v[200:203], v[8:11]
	v_mfma_f32_16x16x32_bf16 v[12:15], v[134:137], v[200:203], v[12:15]
	s_setprio 0
	s_setprio 1
	v_mfma_f32_16x16x32_bf16 v[54:57], v[146:149], v[162:165], v[54:57]
	v_mfma_f32_16x16x32_bf16 v[50:53], v[154:157], v[162:165], v[50:53]
	v_mfma_f32_16x16x32_bf16 v[34:37], v[154:157], v[170:173], v[34:37]
	v_mfma_f32_16x16x32_bf16 v[38:41], v[146:149], v[170:173], v[38:41]
	v_mfma_f32_16x16x32_bf16 v[20:23], v[146:149], v[188:191], v[20:23]
	v_mfma_f32_16x16x32_bf16 v[16:19], v[154:157], v[188:191], v[16:19]
	v_mfma_f32_16x16x32_bf16 v[0:3], v[154:157], v[196:199], v[0:3]
	v_mfma_f32_16x16x32_bf16 v[4:7], v[146:149], v[196:199], v[4:7]
	v_mfma_f32_16x16x32_bf16 v[54:57], v[150:153], v[166:169], v[54:57]
	v_mfma_f32_16x16x32_bf16 v[50:53], v[158:161], v[166:169], v[50:53]
	v_mfma_f32_16x16x32_bf16 v[34:37], v[158:161], v[174:177], v[34:37]
	v_mfma_f32_16x16x32_bf16 v[38:41], v[150:153], v[174:177], v[38:41]
	v_mfma_f32_16x16x32_bf16 v[20:23], v[150:153], v[192:195], v[20:23]
	v_mfma_f32_16x16x32_bf16 v[16:19], v[158:161], v[192:195], v[16:19]
	v_mfma_f32_16x16x32_bf16 v[0:3], v[158:161], v[200:203], v[0:3]
	v_mfma_f32_16x16x32_bf16 v[4:7], v[150:153], v[200:203], v[4:7]
	s_setprio 0
	s_barrier
	s_add_i32 s53, s53, 2
	s_add_u32 s40, s40, 0x100
	s_addc_u32 s41, s41, 0
	s_add_u32 s51, s51, 0x100
	s_addc_u32 s52, s52, 0
	s_cmp_gt_u32 s53, 29
	s_cbranch_scc0 .LBB0_120
	s_and_b64 vcc, exec, s[18:19]
	s_cbranch_vccz .LBB0_123
	s_barrier

.LBB0_685:
	s_add_u32 s28, s16, s40
	s_addc_u32 s29, s17, s41
	s_add_u32 s28, s28, 0x100
	s_addc_u32 s29, s29, 0
	s_add_u32 s42, s52, s40
	s_addc_u32 s43, s53, s41
	s_add_i32 s56, 0, 0x10000
	s_cmpk_eq_i32 s40, 0xf00
	s_cselect_b32 s29, s39, s29
	s_cselect_b32 s28, s38, s28
	s_cselect_b32 s43, s23, s43
	s_cselect_b32 s42, s54, s42
	s_add_i32 s58, 0, 0x14000
	v_add_u32_e32 v146, s56, v190
	v_add_u32_e32 v162, s58, v190
	ds_read_b128 v[134:137], v146
	ds_read_b128 v[138:141], v146 offset:1024
	ds_read_b128 v[142:145], v146 offset:2048
	ds_read_b128 v[146:149], v146 offset:3072
	ds_read_b128 v[150:153], v162
	ds_read_b128 v[154:157], v162 offset:1024
	ds_read_b128 v[158:161], v162 offset:2048
	ds_read_b128 v[162:165], v162 offset:3072
	v_lshl_add_u64 v[212:213], v[130:131], 0, s[40:41]
	s_add_i32 m0, s24, 0xc000
	ds_read_b128 v[166:169], v191
	ds_read_b128 v[180:183], v191 offset:1024
	ds_read_b128 v[184:187], v191 offset:2048
	ds_read_b128 v[192:195], v191 offset:3072
	ds_read_b128 v[196:199], v191 offset:4096
	ds_read_b128 v[200:203], v191 offset:5120
	ds_read_b128 v[204:207], v191 offset:6144
	ds_read_b128 v[208:211], v191 offset:7168
	global_load_lds_dwordx4 v[212:213], off
	v_lshl_add_u64 v[212:213], v[132:133], 0, s[40:41]
	s_add_i32 m0, s24, 0xe000
	s_nop 0
	global_load_lds_dwordx4 v[212:213], off
	s_waitcnt vmcnt(8)
	s_waitcnt lgkmcnt(0)
	s_barrier
	s_setprio 1
	s_waitcnt lgkmcnt(0)
	v_mfma_f32_16x16x32_bf16 v[82:85], v[134:137], v[166:169], v[82:85]
	v_mfma_f32_16x16x32_bf16 v[78:81], v[142:145], v[166:169], v[78:81]
	v_mfma_f32_16x16x32_bf16 v[70:73], v[142:145], v[184:187], v[70:73]
	v_mfma_f32_16x16x32_bf16 v[74:77], v[134:137], v[184:187], v[74:77]
	v_mfma_f32_16x16x32_bf16 v[66:69], v[134:137], v[196:199], v[66:69]
	v_mfma_f32_16x16x32_bf16 v[62:65], v[142:145], v[196:199], v[62:65]
	v_mfma_f32_16x16x32_bf16 v[54:57], v[142:145], v[204:207], v[54:57]
	v_mfma_f32_16x16x32_bf16 v[58:61], v[134:137], v[204:207], v[58:61]
	v_mfma_f32_16x16x32_bf16 v[82:85], v[138:141], v[180:183], v[82:85]
	v_mfma_f32_16x16x32_bf16 v[78:81], v[146:149], v[180:183], v[78:81]
	v_mfma_f32_16x16x32_bf16 v[70:73], v[146:149], v[192:195], v[70:73]
	v_mfma_f32_16x16x32_bf16 v[74:77], v[138:141], v[192:195], v[74:77]
	v_mfma_f32_16x16x32_bf16 v[66:69], v[138:141], v[200:203], v[66:69]
	v_mfma_f32_16x16x32_bf16 v[62:65], v[146:149], v[200:203], v[62:65]
	v_mfma_f32_16x16x32_bf16 v[54:57], v[146:149], v[208:211], v[54:57]
	v_mfma_f32_16x16x32_bf16 v[58:61], v[138:141], v[208:211], v[58:61]
	s_setprio 0
	s_setprio 1
	v_mfma_f32_16x16x32_bf16 v[50:53], v[150:153], v[166:169], v[50:53]
	v_mfma_f32_16x16x32_bf16 v[46:49], v[158:161], v[166:169], v[46:49]
	v_mfma_f32_16x16x32_bf16 v[38:41], v[158:161], v[184:187], v[38:41]
	v_mfma_f32_16x16x32_bf16 v[42:45], v[150:153], v[184:187], v[42:45]
	v_mfma_f32_16x16x32_bf16 v[34:37], v[150:153], v[196:199], v[34:37]
	v_mfma_f32_16x16x32_bf16 v[28:31], v[158:161], v[196:199], v[28:31]
	v_mfma_f32_16x16x32_bf16 v[20:23], v[158:161], v[204:207], v[20:23]
	v_mfma_f32_16x16x32_bf16 v[24:27], v[150:153], v[204:207], v[24:27]
	v_mfma_f32_16x16x32_bf16 v[50:53], v[154:157], v[180:183], v[50:53]
	v_mfma_f32_16x16x32_bf16 v[46:49], v[162:165], v[180:183], v[46:49]
	v_mfma_f32_16x16x32_bf16 v[38:41], v[162:165], v[192:195], v[38:41]
	v_mfma_f32_16x16x32_bf16 v[42:45], v[154:157], v[192:195], v[42:45]
	v_mfma_f32_16x16x32_bf16 v[34:37], v[154:157], v[200:203], v[34:37]
	v_mfma_f32_16x16x32_bf16 v[28:31], v[162:165], v[200:203], v[28:31]
	v_mfma_f32_16x16x32_bf16 v[20:23], v[162:165], v[208:211], v[20:23]
	v_mfma_f32_16x16x32_bf16 v[24:27], v[154:157], v[208:211], v[24:27]
	s_setprio 0
	s_barrier
	s_add_i32 s56, s56, s13
	v_lshl_add_u64 v[212:213], s[42:43], 0, v[32:33]
	s_mov_b32 m0, s56
	ds_read_b128 v[166:169], v191 offset:16384
	ds_read_b128 v[180:183], v191 offset:17408
	ds_read_b128 v[184:187], v191 offset:18432
	ds_read_b128 v[192:195], v191 offset:19456
	ds_read_b128 v[196:199], v191 offset:20480
	ds_read_b128 v[200:203], v191 offset:21504
	ds_read_b128 v[204:207], v191 offset:22528
	ds_read_b128 v[208:211], v191 offset:23552
	global_load_lds_dwordx4 v[212:213], off
	s_add_i32 m0, s56, 0x2000
	s_add_u32 s56, s42, 0x80000
	v_lshl_add_u64 v[214:215], s[42:43], 0, v[174:175]
	s_addc_u32 s57, s43, 0
	s_add_i32 s58, s58, s13
	global_load_lds_dwordx4 v[214:215], off
	v_lshl_add_u64 v[216:217], s[56:57], 0, v[32:33]
	s_mov_b32 m0, s58
	v_lshl_add_u64 v[220:221], s[28:29], 0, v[172:173]
	global_load_lds_dwordx4 v[216:217], off
	v_lshl_add_u64 v[216:217], s[56:57], 0, v[174:175]
	s_add_i32 m0, s58, 0x2000
	s_nop 0
	global_load_lds_dwordx4 v[216:217], off
	v_lshl_add_u64 v[216:217], s[28:29], 0, v[170:171]
	s_mov_b32 m0, s24
	s_nop 0
	global_load_lds_dwordx4 v[216:217], off
	s_mov_b32 m0, s25
	s_nop 0
	global_load_lds_dwordx4 v[220:221], off
	s_waitcnt vmcnt(8)
	s_waitcnt lgkmcnt(0)
	s_barrier
	s_setprio 1
	s_waitcnt lgkmcnt(0)
	v_mfma_f32_16x16x32_bf16 v[16:19], v[134:137], v[166:169], v[16:19]
	v_mfma_f32_16x16x32_bf16 v[12:15], v[142:145], v[166:169], v[12:15]
	v_mfma_f32_16x16x32_bf16 v[4:7], v[142:145], v[184:187], v[4:7]
	v_mfma_f32_16x16x32_bf16 v[8:11], v[134:137], v[184:187], v[8:11]
	v_mfma_f32_16x16x32_bf16 v[0:3], v[134:137], v[196:199], v[0:3]
	v_mfma_f32_16x16x32_bf16 v[86:89], v[142:145], v[196:199], v[86:89]
	v_mfma_f32_16x16x32_bf16 v[94:97], v[142:145], v[204:207], v[94:97]
	v_mfma_f32_16x16x32_bf16 v[90:93], v[134:137], v[204:207], v[90:93]
	v_mfma_f32_16x16x32_bf16 v[16:19], v[138:141], v[180:183], v[16:19]
	v_mfma_f32_16x16x32_bf16 v[12:15], v[146:149], v[180:183], v[12:15]
	v_mfma_f32_16x16x32_bf16 v[4:7], v[146:149], v[192:195], v[4:7]
	v_mfma_f32_16x16x32_bf16 v[8:11], v[138:141], v[192:195], v[8:11]
	v_mfma_f32_16x16x32_bf16 v[0:3], v[138:141], v[200:203], v[0:3]
	v_mfma_f32_16x16x32_bf16 v[86:89], v[146:149], v[200:203], v[86:89]
	v_mfma_f32_16x16x32_bf16 v[94:97], v[146:149], v[208:211], v[94:97]
	v_mfma_f32_16x16x32_bf16 v[90:93], v[138:141], v[208:211], v[90:93]
	s_setprio 0
	s_setprio 1
	v_mfma_f32_16x16x32_bf16 v[98:101], v[150:153], v[166:169], v[98:101]
	v_mfma_f32_16x16x32_bf16 v[102:105], v[158:161], v[166:169], v[102:105]
	v_mfma_f32_16x16x32_bf16 v[110:113], v[158:161], v[184:187], v[110:113]
	v_mfma_f32_16x16x32_bf16 v[106:109], v[150:153], v[184:187], v[106:109]
	v_mfma_f32_16x16x32_bf16 v[114:117], v[150:153], v[196:199], v[114:117]
	v_mfma_f32_16x16x32_bf16 v[118:121], v[158:161], v[196:199], v[118:121]
	v_mfma_f32_16x16x32_bf16 v[126:129], v[158:161], v[204:207], v[126:129]
	v_mfma_f32_16x16x32_bf16 v[122:125], v[150:153], v[204:207], v[122:125]
	v_mfma_f32_16x16x32_bf16 v[98:101], v[154:157], v[180:183], v[98:101]
	v_mfma_f32_16x16x32_bf16 v[102:105], v[162:165], v[180:183], v[102:105]
	v_mfma_f32_16x16x32_bf16 v[110:113], v[162:165], v[192:195], v[110:113]
	v_mfma_f32_16x16x32_bf16 v[106:109], v[154:157], v[192:195], v[106:109]
	v_mfma_f32_16x16x32_bf16 v[114:117], v[154:157], v[200:203], v[114:117]
	v_mfma_f32_16x16x32_bf16 v[118:121], v[162:165], v[200:203], v[118:121]
	v_mfma_f32_16x16x32_bf16 v[126:129], v[162:165], v[208:211], v[126:129]
	v_mfma_f32_16x16x32_bf16 v[122:125], v[154:157], v[208:211], v[122:125]
	s_setprio 0
	s_barrier
	s_add_i32 s56, 0, 0x18000
	s_add_i32 s57, 0, 0x1c000
	v_add_u32_e32 v146, s56, v190
	v_add_u32_e32 v162, s57, v190
	ds_read_b128 v[134:137], v146
	ds_read_b128 v[138:141], v146 offset:1024
	ds_read_b128 v[142:145], v146 offset:2048
	ds_read_b128 v[146:149], v146 offset:3072
	ds_read_b128 v[150:153], v162
	ds_read_b128 v[154:157], v162 offset:1024
	ds_read_b128 v[158:161], v162 offset:2048
	ds_read_b128 v[162:165], v162 offset:3072
	s_add_u32 s28, s28, 0x80000
	s_addc_u32 s29, s29, 0
	s_mov_b32 m0, s33
	v_lshl_add_u64 v[222:223], s[28:29], 0, v[170:171]
	ds_read_b128 v[166:169], v191 offset:32768
	ds_read_b128 v[180:183], v191 offset:33792
	ds_read_b128 v[184:187], v191 offset:34816
	ds_read_b128 v[192:195], v191 offset:35840
	ds_read_b128 v[196:199], v191 offset:36864
	ds_read_b128 v[200:203], v191 offset:37888
	ds_read_b128 v[204:207], v191 offset:38912
	ds_read_b128 v[208:211], v191 offset:39936
	global_load_lds_dwordx4 v[222:223], off
	v_lshl_add_u64 v[222:223], s[28:29], 0, v[172:173]
	s_mov_b32 m0, s36
	s_nop 0
	global_load_lds_dwordx4 v[222:223], off
	s_waitcnt vmcnt(8)
	s_waitcnt lgkmcnt(0)
	s_barrier
	s_setprio 1
	s_waitcnt lgkmcnt(0)
	v_mfma_f32_16x16x32_bf16 v[82:85], v[134:137], v[166:169], v[82:85]
	v_mfma_f32_16x16x32_bf16 v[78:81], v[142:145], v[166:169], v[78:81]
	v_mfma_f32_16x16x32_bf16 v[70:73], v[142:145], v[184:187], v[70:73]
	v_mfma_f32_16x16x32_bf16 v[74:77], v[134:137], v[184:187], v[74:77]
	v_mfma_f32_16x16x32_bf16 v[66:69], v[134:137], v[196:199], v[66:69]
	v_mfma_f32_16x16x32_bf16 v[62:65], v[142:145], v[196:199], v[62:65]
	v_mfma_f32_16x16x32_bf16 v[54:57], v[142:145], v[204:207], v[54:57]
	v_mfma_f32_16x16x32_bf16 v[58:61], v[134:137], v[204:207], v[58:61]
	v_mfma_f32_16x16x32_bf16 v[82:85], v[138:141], v[180:183], v[82:85]
	v_mfma_f32_16x16x32_bf16 v[78:81], v[146:149], v[180:183], v[78:81]
	v_mfma_f32_16x16x32_bf16 v[70:73], v[146:149], v[192:195], v[70:73]
	v_mfma_f32_16x16x32_bf16 v[74:77], v[138:141], v[192:195], v[74:77]
	v_mfma_f32_16x16x32_bf16 v[66:69], v[138:141], v[200:203], v[66:69]
	v_mfma_f32_16x16x32_bf16 v[62:65], v[146:149], v[200:203], v[62:65]
	v_mfma_f32_16x16x32_bf16 v[54:57], v[146:149], v[208:211], v[54:57]
	v_mfma_f32_16x16x32_bf16 v[58:61], v[138:141], v[208:211], v[58:61]
	s_setprio 0
	s_setprio 1
	v_mfma_f32_16x16x32_bf16 v[50:53], v[150:153], v[166:169], v[50:53]
	v_mfma_f32_16x16x32_bf16 v[46:49], v[158:161], v[166:169], v[46:49]
	v_mfma_f32_16x16x32_bf16 v[38:41], v[158:161], v[184:187], v[38:41]
	v_mfma_f32_16x16x32_bf16 v[42:45], v[150:153], v[184:187], v[42:45]
	v_mfma_f32_16x16x32_bf16 v[34:37], v[150:153], v[196:199], v[34:37]
	v_mfma_f32_16x16x32_bf16 v[28:31], v[158:161], v[196:199], v[28:31]
	v_mfma_f32_16x16x32_bf16 v[20:23], v[158:161], v[204:207], v[20:23]
	v_mfma_f32_16x16x32_bf16 v[24:27], v[150:153], v[204:207], v[24:27]
	v_mfma_f32_16x16x32_bf16 v[50:53], v[154:157], v[180:183], v[50:53]
	v_mfma_f32_16x16x32_bf16 v[46:49], v[162:165], v[180:183], v[46:49]
	v_mfma_f32_16x16x32_bf16 v[38:41], v[162:165], v[192:195], v[38:41]
	v_mfma_f32_16x16x32_bf16 v[42:45], v[154:157], v[192:195], v[42:45]
	v_mfma_f32_16x16x32_bf16 v[34:37], v[154:157], v[200:203], v[34:37]
	v_mfma_f32_16x16x32_bf16 v[28:31], v[162:165], v[200:203], v[28:31]
	v_mfma_f32_16x16x32_bf16 v[20:23], v[162:165], v[208:211], v[20:23]
	v_mfma_f32_16x16x32_bf16 v[24:27], v[154:157], v[208:211], v[24:27]
	s_setprio 0
	s_barrier
	s_add_i32 s28, s56, s13
	v_lshl_add_u64 v[212:213], v[212:213], 0, s[34:35]
	s_mov_b32 m0, s28
	ds_read_b128 v[166:169], v191 offset:49152
	ds_read_b128 v[180:183], v191 offset:50176
	ds_read_b128 v[184:187], v191 offset:51200
	ds_read_b128 v[192:195], v191 offset:52224
	ds_read_b128 v[196:199], v191 offset:53248
	ds_read_b128 v[200:203], v191 offset:54272
	ds_read_b128 v[204:207], v191 offset:55296
	ds_read_b128 v[208:211], v191 offset:56320
	global_load_lds_dwordx4 v[212:213], off
	s_add_i32 m0, s28, 0x2000
	s_add_u32 s28, s42, 0x80080
	v_lshl_add_u64 v[212:213], v[214:215], 0, s[34:35]
	s_addc_u32 s29, s43, 0
	s_add_i32 s42, s57, s13
	global_load_lds_dwordx4 v[212:213], off
	v_lshl_add_u64 v[212:213], s[28:29], 0, v[32:33]
	s_mov_b32 m0, s42
	s_nop 0
	global_load_lds_dwordx4 v[212:213], off
	v_lshl_add_u64 v[212:213], s[28:29], 0, v[174:175]
	s_add_i32 m0, s42, 0x2000
	s_nop 0
	global_load_lds_dwordx4 v[212:213], off
	v_lshl_add_u64 v[212:213], v[216:217], 0, s[34:35]
	s_mov_b32 m0, s45
	s_nop 0
	global_load_lds_dwordx4 v[212:213], off
	v_lshl_add_u64 v[212:213], v[220:221], 0, s[34:35]
	s_mov_b32 m0, s46
	s_nop 0
	global_load_lds_dwordx4 v[212:213], off
	s_waitcnt vmcnt(8)
	s_waitcnt lgkmcnt(0)
	s_barrier
	s_setprio 1
	s_waitcnt lgkmcnt(0)
	v_mfma_f32_16x16x32_bf16 v[16:19], v[134:137], v[166:169], v[16:19]
	v_mfma_f32_16x16x32_bf16 v[12:15], v[142:145], v[166:169], v[12:15]
	v_mfma_f32_16x16x32_bf16 v[4:7], v[142:145], v[184:187], v[4:7]
	v_mfma_f32_16x16x32_bf16 v[8:11], v[134:137], v[184:187], v[8:11]
	v_mfma_f32_16x16x32_bf16 v[0:3], v[134:137], v[196:199], v[0:3]
	v_mfma_f32_16x16x32_bf16 v[86:89], v[142:145], v[196:199], v[86:89]
	v_mfma_f32_16x16x32_bf16 v[94:97], v[142:145], v[204:207], v[94:97]
	v_mfma_f32_16x16x32_bf16 v[90:93], v[134:137], v[204:207], v[90:93]
	v_mfma_f32_16x16x32_bf16 v[16:19], v[138:141], v[180:183], v[16:19]
	v_mfma_f32_16x16x32_bf16 v[12:15], v[146:149], v[180:183], v[12:15]
	v_mfma_f32_16x16x32_bf16 v[4:7], v[146:149], v[192:195], v[4:7]
	v_mfma_f32_16x16x32_bf16 v[8:11], v[138:141], v[192:195], v[8:11]
	v_mfma_f32_16x16x32_bf16 v[0:3], v[138:141], v[200:203], v[0:3]
	v_mfma_f32_16x16x32_bf16 v[86:89], v[146:149], v[200:203], v[86:89]
	v_mfma_f32_16x16x32_bf16 v[94:97], v[146:149], v[208:211], v[94:97]
	v_mfma_f32_16x16x32_bf16 v[90:93], v[138:141], v[208:211], v[90:93]
	s_setprio 0
	s_setprio 1
	v_mfma_f32_16x16x32_bf16 v[98:101], v[150:153], v[166:169], v[98:101]
	v_mfma_f32_16x16x32_bf16 v[102:105], v[158:161], v[166:169], v[102:105]
	v_mfma_f32_16x16x32_bf16 v[110:113], v[158:161], v[184:187], v[110:113]
	v_mfma_f32_16x16x32_bf16 v[106:109], v[150:153], v[184:187], v[106:109]
	v_mfma_f32_16x16x32_bf16 v[114:117], v[150:153], v[196:199], v[114:117]
	v_mfma_f32_16x16x32_bf16 v[118:121], v[158:161], v[196:199], v[118:121]
	v_mfma_f32_16x16x32_bf16 v[126:129], v[158:161], v[204:207], v[126:129]
	v_mfma_f32_16x16x32_bf16 v[122:125], v[150:153], v[204:207], v[122:125]
	v_mfma_f32_16x16x32_bf16 v[98:101], v[154:157], v[180:183], v[98:101]
	v_mfma_f32_16x16x32_bf16 v[102:105], v[162:165], v[180:183], v[102:105]
	v_mfma_f32_16x16x32_bf16 v[110:113], v[162:165], v[192:195], v[110:113]
	v_mfma_f32_16x16x32_bf16 v[106:109], v[154:157], v[192:195], v[106:109]
	v_mfma_f32_16x16x32_bf16 v[114:117], v[154:157], v[200:203], v[114:117]
	v_mfma_f32_16x16x32_bf16 v[118:121], v[162:165], v[200:203], v[118:121]
	v_mfma_f32_16x16x32_bf16 v[126:129], v[162:165], v[208:211], v[126:129]
	v_mfma_f32_16x16x32_bf16 v[122:125], v[154:157], v[208:211], v[122:125]
	s_setprio 0
	s_barrier
	s_add_i32 s55, s55, 2
	s_add_u32 s40, s40, 0x100
	s_addc_u32 s41, s41, 0
	s_cmp_gt_u32 s55, 29
	s_cbranch_scc0 .LBB0_685
	s_and_b64 vcc, exec, s[18:19]
	s_cbranch_vccz .LBB0_688
	s_barrier

.LBB0_755:
	s_add_u32 s6, s4, 0x100
	s_addc_u32 s7, s5, 0
	s_add_i32 s52, 0, 0x10000
	s_cmpk_eq_i32 s51, 0x54
	s_cselect_b32 s29, s23, s7
	s_cselect_b32 s28, s22, s6
	s_cselect_b32 s31, s27, s50
	s_cselect_b32 s30, s26, s33
	s_add_i32 s53, 0, 0x14000
	v_add_u32_e32 v142, s52, v242
	v_add_u32_e32 v158, s53, v242
	ds_read_b128 v[130:133], v142
	ds_read_b128 v[134:137], v142 offset:1024
	ds_read_b128 v[138:141], v142 offset:2048
	ds_read_b128 v[142:145], v142 offset:3072
	ds_read_b128 v[146:149], v158
	ds_read_b128 v[150:153], v158 offset:1024
	ds_read_b128 v[154:157], v158 offset:2048
	ds_read_b128 v[158:161], v158 offset:3072
	v_lshl_add_u64 v[194:195], s[4:5], 0, v[202:203]
	s_add_i32 m0, s36, 0xc000
	ds_read_b128 v[162:165], v243
	ds_read_b128 v[166:169], v243 offset:1024
	ds_read_b128 v[170:173], v243 offset:2048
	ds_read_b128 v[174:177], v243 offset:3072
	ds_read_b128 v[178:181], v243 offset:4096
	ds_read_b128 v[182:185], v243 offset:5120
	ds_read_b128 v[186:189], v243 offset:6144
	ds_read_b128 v[190:193], v243 offset:7168
	global_load_lds_dwordx4 v[194:195], off
	v_lshl_add_u64 v[194:195], s[4:5], 0, v[204:205]
	s_add_i32 m0, s36, 0xe000
	s_nop 0
	global_load_lds_dwordx4 v[194:195], off
	s_waitcnt vmcnt(8)
	s_waitcnt lgkmcnt(0)
	s_barrier
	s_setprio 1
	s_waitcnt lgkmcnt(0)
	v_mfma_f32_16x16x32_bf16 v[126:129], v[130:133], v[162:165], v[126:129]
	v_mfma_f32_16x16x32_bf16 v[122:125], v[138:141], v[162:165], v[122:125]
	v_mfma_f32_16x16x32_bf16 v[106:109], v[138:141], v[170:173], v[106:109]
	v_mfma_f32_16x16x32_bf16 v[110:113], v[130:133], v[170:173], v[110:113]
	v_mfma_f32_16x16x32_bf16 v[94:97], v[130:133], v[178:181], v[94:97]
	v_mfma_f32_16x16x32_bf16 v[90:93], v[138:141], v[178:181], v[90:93]
	v_mfma_f32_16x16x32_bf16 v[74:77], v[138:141], v[186:189], v[74:77]
	v_mfma_f32_16x16x32_bf16 v[78:81], v[130:133], v[186:189], v[78:81]
	v_mfma_f32_16x16x32_bf16 v[126:129], v[134:137], v[166:169], v[126:129]
	v_mfma_f32_16x16x32_bf16 v[122:125], v[142:145], v[166:169], v[122:125]
	v_mfma_f32_16x16x32_bf16 v[106:109], v[142:145], v[174:177], v[106:109]
	v_mfma_f32_16x16x32_bf16 v[110:113], v[134:137], v[174:177], v[110:113]
	v_mfma_f32_16x16x32_bf16 v[94:97], v[134:137], v[182:185], v[94:97]
	v_mfma_f32_16x16x32_bf16 v[90:93], v[142:145], v[182:185], v[90:93]
	v_mfma_f32_16x16x32_bf16 v[74:77], v[142:145], v[190:193], v[74:77]
	v_mfma_f32_16x16x32_bf16 v[78:81], v[134:137], v[190:193], v[78:81]
	s_setprio 0
	s_setprio 1
	v_mfma_f32_16x16x32_bf16 v[118:121], v[146:149], v[162:165], v[118:121]
	v_mfma_f32_16x16x32_bf16 v[114:117], v[154:157], v[162:165], v[114:117]
	v_mfma_f32_16x16x32_bf16 v[98:101], v[154:157], v[170:173], v[98:101]
	v_mfma_f32_16x16x32_bf16 v[102:105], v[146:149], v[170:173], v[102:105]
	v_mfma_f32_16x16x32_bf16 v[86:89], v[146:149], v[178:181], v[86:89]
	v_mfma_f32_16x16x32_bf16 v[82:85], v[154:157], v[178:181], v[82:85]
	v_mfma_f32_16x16x32_bf16 v[66:69], v[154:157], v[186:189], v[66:69]
	v_mfma_f32_16x16x32_bf16 v[70:73], v[146:149], v[186:189], v[70:73]
	v_mfma_f32_16x16x32_bf16 v[118:121], v[150:153], v[166:169], v[118:121]
	v_mfma_f32_16x16x32_bf16 v[114:117], v[158:161], v[166:169], v[114:117]
	v_mfma_f32_16x16x32_bf16 v[98:101], v[158:161], v[174:177], v[98:101]
	v_mfma_f32_16x16x32_bf16 v[102:105], v[150:153], v[174:177], v[102:105]
	v_mfma_f32_16x16x32_bf16 v[86:89], v[150:153], v[182:185], v[86:89]
	v_mfma_f32_16x16x32_bf16 v[82:85], v[158:161], v[182:185], v[82:85]
	v_mfma_f32_16x16x32_bf16 v[66:69], v[158:161], v[190:193], v[66:69]
	v_mfma_f32_16x16x32_bf16 v[70:73], v[150:153], v[190:193], v[70:73]
	s_setprio 0
	s_barrier
	s_add_i32 s4, s52, s1
	v_lshl_add_u64 v[194:195], s[30:31], 0, v[32:33]
	s_mov_b32 m0, s4
	ds_read_b128 v[162:165], v243 offset:16384
	ds_read_b128 v[166:169], v243 offset:17408
	ds_read_b128 v[170:173], v243 offset:18432
	ds_read_b128 v[174:177], v243 offset:19456
	ds_read_b128 v[178:181], v243 offset:20480
	ds_read_b128 v[182:185], v243 offset:21504
	ds_read_b128 v[186:189], v243 offset:22528
	ds_read_b128 v[190:193], v243 offset:23552
	global_load_lds_dwordx4 v[194:195], off
	s_add_i32 m0, s4, 0x2000
	s_add_u32 s4, s30, 0x160000
	v_lshl_add_u64 v[206:207], s[30:31], 0, v[200:201]
	s_addc_u32 s5, s31, 0
	s_add_i32 s52, s53, s1
	global_load_lds_dwordx4 v[206:207], off
	v_lshl_add_u64 v[208:209], s[4:5], 0, v[32:33]
	s_mov_b32 m0, s52
	v_lshl_add_u64 v[210:211], s[28:29], 0, v[198:199]
	global_load_lds_dwordx4 v[208:209], off
	v_lshl_add_u64 v[208:209], s[4:5], 0, v[200:201]
	s_add_i32 m0, s52, 0x2000
	s_nop 0
	global_load_lds_dwordx4 v[208:209], off
	v_lshl_add_u64 v[208:209], s[28:29], 0, v[196:197]
	s_mov_b32 m0, s36
	s_nop 0
	global_load_lds_dwordx4 v[208:209], off
	s_mov_b32 m0, s38
	s_nop 0
	global_load_lds_dwordx4 v[210:211], off
	s_waitcnt vmcnt(8)
	s_waitcnt lgkmcnt(0)
	s_barrier
	s_setprio 1
	s_waitcnt lgkmcnt(0)
	v_mfma_f32_16x16x32_bf16 v[62:65], v[130:133], v[162:165], v[62:65]
	v_mfma_f32_16x16x32_bf16 v[58:61], v[138:141], v[162:165], v[58:61]
	v_mfma_f32_16x16x32_bf16 v[42:45], v[138:141], v[170:173], v[42:45]
	v_mfma_f32_16x16x32_bf16 v[46:49], v[130:133], v[170:173], v[46:49]
	v_mfma_f32_16x16x32_bf16 v[28:31], v[130:133], v[178:181], v[28:31]
	v_mfma_f32_16x16x32_bf16 v[24:27], v[138:141], v[178:181], v[24:27]
	v_mfma_f32_16x16x32_bf16 v[8:11], v[138:141], v[186:189], v[8:11]
	v_mfma_f32_16x16x32_bf16 v[12:15], v[130:133], v[186:189], v[12:15]
	v_mfma_f32_16x16x32_bf16 v[62:65], v[134:137], v[166:169], v[62:65]
	v_mfma_f32_16x16x32_bf16 v[58:61], v[142:145], v[166:169], v[58:61]
	v_mfma_f32_16x16x32_bf16 v[42:45], v[142:145], v[174:177], v[42:45]
	v_mfma_f32_16x16x32_bf16 v[46:49], v[134:137], v[174:177], v[46:49]
	v_mfma_f32_16x16x32_bf16 v[28:31], v[134:137], v[182:185], v[28:31]
	v_mfma_f32_16x16x32_bf16 v[24:27], v[142:145], v[182:185], v[24:27]
	v_mfma_f32_16x16x32_bf16 v[8:11], v[142:145], v[190:193], v[8:11]
	v_mfma_f32_16x16x32_bf16 v[12:15], v[134:137], v[190:193], v[12:15]
	s_setprio 0
	s_setprio 1
	v_mfma_f32_16x16x32_bf16 v[54:57], v[146:149], v[162:165], v[54:57]
	v_mfma_f32_16x16x32_bf16 v[50:53], v[154:157], v[162:165], v[50:53]
	v_mfma_f32_16x16x32_bf16 v[34:37], v[154:157], v[170:173], v[34:37]
	v_mfma_f32_16x16x32_bf16 v[38:41], v[146:149], v[170:173], v[38:41]
	v_mfma_f32_16x16x32_bf16 v[20:23], v[146:149], v[178:181], v[20:23]
	v_mfma_f32_16x16x32_bf16 v[16:19], v[154:157], v[178:181], v[16:19]
	v_mfma_f32_16x16x32_bf16 v[0:3], v[154:157], v[186:189], v[0:3]
	v_mfma_f32_16x16x32_bf16 v[4:7], v[146:149], v[186:189], v[4:7]
	v_mfma_f32_16x16x32_bf16 v[54:57], v[150:153], v[166:169], v[54:57]
	v_mfma_f32_16x16x32_bf16 v[50:53], v[158:161], v[166:169], v[50:53]
	v_mfma_f32_16x16x32_bf16 v[34:37], v[158:161], v[174:177], v[34:37]
	v_mfma_f32_16x16x32_bf16 v[38:41], v[150:153], v[174:177], v[38:41]
	v_mfma_f32_16x16x32_bf16 v[20:23], v[150:153], v[182:185], v[20:23]
	v_mfma_f32_16x16x32_bf16 v[16:19], v[158:161], v[182:185], v[16:19]
	v_mfma_f32_16x16x32_bf16 v[0:3], v[158:161], v[190:193], v[0:3]
	v_mfma_f32_16x16x32_bf16 v[4:7], v[150:153], v[190:193], v[4:7]
	s_setprio 0
	s_barrier
	s_add_i32 s52, 0, 0x18000
	s_add_i32 s53, 0, 0x1c000
	v_add_u32_e32 v142, s52, v242
	v_add_u32_e32 v158, s53, v242
	ds_read_b128 v[130:133], v142
	ds_read_b128 v[134:137], v142 offset:1024
	ds_read_b128 v[138:141], v142 offset:2048
	ds_read_b128 v[142:145], v142 offset:3072
	ds_read_b128 v[146:149], v158
	ds_read_b128 v[150:153], v158 offset:1024
	ds_read_b128 v[154:157], v158 offset:2048
	ds_read_b128 v[158:161], v158 offset:3072
	s_add_u32 s4, s28, 0x160000
	s_addc_u32 s5, s29, 0
	s_mov_b32 m0, s39
	v_lshl_add_u64 v[212:213], s[4:5], 0, v[196:197]
	ds_read_b128 v[162:165], v243 offset:32768
	ds_read_b128 v[166:169], v243 offset:33792
	ds_read_b128 v[170:173], v243 offset:34816
	ds_read_b128 v[174:177], v243 offset:35840
	ds_read_b128 v[178:181], v243 offset:36864
	ds_read_b128 v[182:185], v243 offset:37888
	ds_read_b128 v[186:189], v243 offset:38912
	ds_read_b128 v[190:193], v243 offset:39936
	global_load_lds_dwordx4 v[212:213], off
	v_lshl_add_u64 v[212:213], s[4:5], 0, v[198:199]
	s_mov_b32 m0, s42
	s_nop 0
	global_load_lds_dwordx4 v[212:213], off
	s_waitcnt vmcnt(8)
	s_waitcnt lgkmcnt(0)
	s_barrier
	s_setprio 1
	s_waitcnt lgkmcnt(0)
	v_mfma_f32_16x16x32_bf16 v[126:129], v[130:133], v[162:165], v[126:129]
	v_mfma_f32_16x16x32_bf16 v[122:125], v[138:141], v[162:165], v[122:125]
	v_mfma_f32_16x16x32_bf16 v[106:109], v[138:141], v[170:173], v[106:109]
	v_mfma_f32_16x16x32_bf16 v[110:113], v[130:133], v[170:173], v[110:113]
	v_mfma_f32_16x16x32_bf16 v[94:97], v[130:133], v[178:181], v[94:97]
	v_mfma_f32_16x16x32_bf16 v[90:93], v[138:141], v[178:181], v[90:93]
	v_mfma_f32_16x16x32_bf16 v[74:77], v[138:141], v[186:189], v[74:77]
	v_mfma_f32_16x16x32_bf16 v[78:81], v[130:133], v[186:189], v[78:81]
	v_mfma_f32_16x16x32_bf16 v[126:129], v[134:137], v[166:169], v[126:129]
	v_mfma_f32_16x16x32_bf16 v[122:125], v[142:145], v[166:169], v[122:125]
	v_mfma_f32_16x16x32_bf16 v[106:109], v[142:145], v[174:177], v[106:109]
	v_mfma_f32_16x16x32_bf16 v[110:113], v[134:137], v[174:177], v[110:113]
	v_mfma_f32_16x16x32_bf16 v[94:97], v[134:137], v[182:185], v[94:97]
	v_mfma_f32_16x16x32_bf16 v[90:93], v[142:145], v[182:185], v[90:93]
	v_mfma_f32_16x16x32_bf16 v[74:77], v[142:145], v[190:193], v[74:77]
	v_mfma_f32_16x16x32_bf16 v[78:81], v[134:137], v[190:193], v[78:81]
	s_setprio 0
	s_setprio 1
	v_mfma_f32_16x16x32_bf16 v[118:121], v[146:149], v[162:165], v[118:121]
	v_mfma_f32_16x16x32_bf16 v[114:117], v[154:157], v[162:165], v[114:117]
	v_mfma_f32_16x16x32_bf16 v[98:101], v[154:157], v[170:173], v[98:101]
	v_mfma_f32_16x16x32_bf16 v[102:105], v[146:149], v[170:173], v[102:105]
	v_mfma_f32_16x16x32_bf16 v[86:89], v[146:149], v[178:181], v[86:89]
	v_mfma_f32_16x16x32_bf16 v[82:85], v[154:157], v[178:181], v[82:85]
	v_mfma_f32_16x16x32_bf16 v[66:69], v[154:157], v[186:189], v[66:69]
	v_mfma_f32_16x16x32_bf16 v[70:73], v[146:149], v[186:189], v[70:73]
	v_mfma_f32_16x16x32_bf16 v[118:121], v[150:153], v[166:169], v[118:121]
	v_mfma_f32_16x16x32_bf16 v[114:117], v[158:161], v[166:169], v[114:117]
	v_mfma_f32_16x16x32_bf16 v[98:101], v[158:161], v[174:177], v[98:101]
	v_mfma_f32_16x16x32_bf16 v[102:105], v[150:153], v[174:177], v[102:105]
	v_mfma_f32_16x16x32_bf16 v[86:89], v[150:153], v[182:185], v[86:89]
	v_mfma_f32_16x16x32_bf16 v[82:85], v[158:161], v[182:185], v[82:85]
	v_mfma_f32_16x16x32_bf16 v[66:69], v[158:161], v[190:193], v[66:69]
	v_mfma_f32_16x16x32_bf16 v[70:73], v[150:153], v[190:193], v[70:73]
	s_setprio 0
	s_barrier
	s_add_i32 s4, s52, s1
	v_lshl_add_u64 v[194:195], v[194:195], 0, s[34:35]
	s_mov_b32 m0, s4
	ds_read_b128 v[162:165], v243 offset:49152
	ds_read_b128 v[166:169], v243 offset:50176
	ds_read_b128 v[170:173], v243 offset:51200
	ds_read_b128 v[174:177], v243 offset:52224
	ds_read_b128 v[178:181], v243 offset:53248
	ds_read_b128 v[182:185], v243 offset:54272
	ds_read_b128 v[186:189], v243 offset:55296
	ds_read_b128 v[190:193], v243 offset:56320
	global_load_lds_dwordx4 v[194:195], off
	s_add_i32 m0, s4, 0x2000
	s_add_u32 s4, s30, 0x160080
	v_lshl_add_u64 v[194:195], v[206:207], 0, s[34:35]
	s_addc_u32 s5, s31, 0
	s_add_i32 s28, s53, s1
	global_load_lds_dwordx4 v[194:195], off
	v_lshl_add_u64 v[194:195], s[4:5], 0, v[32:33]
	s_mov_b32 m0, s28
	s_nop 0
	global_load_lds_dwordx4 v[194:195], off
	v_lshl_add_u64 v[194:195], s[4:5], 0, v[200:201]
	s_add_i32 m0, s28, 0x2000
	s_nop 0
	global_load_lds_dwordx4 v[194:195], off
	v_lshl_add_u64 v[194:195], v[208:209], 0, s[34:35]
	s_mov_b32 m0, s44
	s_nop 0
	global_load_lds_dwordx4 v[194:195], off
	v_lshl_add_u64 v[194:195], v[210:211], 0, s[34:35]
	s_mov_b32 m0, s45
	s_nop 0
	global_load_lds_dwordx4 v[194:195], off
	s_waitcnt vmcnt(8)
	s_waitcnt lgkmcnt(0)
	s_barrier
	s_setprio 1
	s_waitcnt lgkmcnt(0)
	v_mfma_f32_16x16x32_bf16 v[62:65], v[130:133], v[162:165], v[62:65]
	v_mfma_f32_16x16x32_bf16 v[58:61], v[138:141], v[162:165], v[58:61]
	v_mfma_f32_16x16x32_bf16 v[42:45], v[138:141], v[170:173], v[42:45]
	v_mfma_f32_16x16x32_bf16 v[46:49], v[130:133], v[170:173], v[46:49]
	v_mfma_f32_16x16x32_bf16 v[28:31], v[130:133], v[178:181], v[28:31]
	v_mfma_f32_16x16x32_bf16 v[24:27], v[138:141], v[178:181], v[24:27]
	v_mfma_f32_16x16x32_bf16 v[8:11], v[138:141], v[186:189], v[8:11]
	v_mfma_f32_16x16x32_bf16 v[12:15], v[130:133], v[186:189], v[12:15]
	v_mfma_f32_16x16x32_bf16 v[62:65], v[134:137], v[166:169], v[62:65]
	v_mfma_f32_16x16x32_bf16 v[58:61], v[142:145], v[166:169], v[58:61]
	v_mfma_f32_16x16x32_bf16 v[42:45], v[142:145], v[174:177], v[42:45]
	v_mfma_f32_16x16x32_bf16 v[46:49], v[134:137], v[174:177], v[46:49]
	v_mfma_f32_16x16x32_bf16 v[28:31], v[134:137], v[182:185], v[28:31]
	v_mfma_f32_16x16x32_bf16 v[24:27], v[142:145], v[182:185], v[24:27]
	v_mfma_f32_16x16x32_bf16 v[8:11], v[142:145], v[190:193], v[8:11]
	v_mfma_f32_16x16x32_bf16 v[12:15], v[134:137], v[190:193], v[12:15]
	s_setprio 0
	s_setprio 1
	v_mfma_f32_16x16x32_bf16 v[54:57], v[146:149], v[162:165], v[54:57]
	v_mfma_f32_16x16x32_bf16 v[50:53], v[154:157], v[162:165], v[50:53]
	v_mfma_f32_16x16x32_bf16 v[34:37], v[154:157], v[170:173], v[34:37]
	v_mfma_f32_16x16x32_bf16 v[38:41], v[146:149], v[170:173], v[38:41]
	v_mfma_f32_16x16x32_bf16 v[20:23], v[146:149], v[178:181], v[20:23]
	v_mfma_f32_16x16x32_bf16 v[16:19], v[154:157], v[178:181], v[16:19]
	v_mfma_f32_16x16x32_bf16 v[0:3], v[154:157], v[186:189], v[0:3]
	v_mfma_f32_16x16x32_bf16 v[4:7], v[146:149], v[186:189], v[4:7]
	v_mfma_f32_16x16x32_bf16 v[54:57], v[150:153], v[166:169], v[54:57]
	v_mfma_f32_16x16x32_bf16 v[50:53], v[158:161], v[166:169], v[50:53]
	v_mfma_f32_16x16x32_bf16 v[34:37], v[158:161], v[174:177], v[34:37]
	v_mfma_f32_16x16x32_bf16 v[38:41], v[150:153], v[174:177], v[38:41]
	v_mfma_f32_16x16x32_bf16 v[20:23], v[150:153], v[182:185], v[20:23]
	v_mfma_f32_16x16x32_bf16 v[16:19], v[158:161], v[182:185], v[16:19]
	v_mfma_f32_16x16x32_bf16 v[0:3], v[158:161], v[190:193], v[0:3]
	v_mfma_f32_16x16x32_bf16 v[4:7], v[150:153], v[190:193], v[4:7]
	s_setprio 0
	s_barrier
	s_add_i32 s51, s51, 2
	s_add_u32 s33, s33, 0x100
	s_addc_u32 s50, s50, 0
	s_cmpk_gt_u32 s51, 0x55
	s_mov_b64 s[4:5], s[6:7]
	s_cbranch_scc0 .LBB0_755
	s_and_b64 vcc, exec, s[18:19]
	s_cbranch_vccz .LBB0_758
	s_barrier

.LBB0_888:
	s_add_u32 s38, s16, s30
	s_addc_u32 s39, s17, s31
	s_add_u32 s38, s38, 0x100
	s_addc_u32 s39, s39, 0
	s_add_u32 s54, s50, s30
	s_addc_u32 s55, s51, s31
	s_add_i32 s56, 0, 0x10000
	s_cmpk_eq_i32 s30, 0xf00
	s_cselect_b32 s41, s29, s39
	s_cselect_b32 s40, s28, s38
	s_cselect_b32 s39, s21, s55
	s_cselect_b32 s38, s52, s54
	s_add_i32 s57, 0, 0x14000
	v_add_u32_e32 v146, s56, v178
	v_add_u32_e32 v172, s57, v178
	ds_read_b128 v[134:137], v146
	ds_read_b128 v[138:141], v146 offset:1024
	ds_read_b128 v[142:145], v146 offset:2048
	ds_read_b128 v[146:149], v146 offset:3072
	ds_read_b128 v[150:153], v172
	ds_read_b128 v[154:157], v172 offset:1024
	ds_read_b128 v[158:161], v172 offset:2048
	ds_read_b128 v[172:175], v172 offset:3072
	v_lshl_add_u64 v[212:213], v[130:131], 0, s[30:31]
	s_add_i32 m0, s24, 0xc000
	ds_read_b128 v[180:183], v179
	ds_read_b128 v[184:187], v179 offset:1024
	ds_read_b128 v[188:191], v179 offset:2048
	ds_read_b128 v[192:195], v179 offset:3072
	ds_read_b128 v[196:199], v179 offset:4096
	ds_read_b128 v[200:203], v179 offset:5120
	ds_read_b128 v[204:207], v179 offset:6144
	ds_read_b128 v[208:211], v179 offset:7168
	global_load_lds_dwordx4 v[212:213], off
	v_lshl_add_u64 v[212:213], v[132:133], 0, s[30:31]
	s_add_i32 m0, s24, 0xe000
	s_nop 0
	global_load_lds_dwordx4 v[212:213], off
	s_waitcnt vmcnt(8)
	s_waitcnt lgkmcnt(0)
	s_barrier
	s_setprio 1
	s_waitcnt lgkmcnt(0)
	v_mfma_f32_16x16x32_bf16 v[82:85], v[134:137], v[180:183], v[82:85]
	v_mfma_f32_16x16x32_bf16 v[78:81], v[142:145], v[180:183], v[78:81]
	v_mfma_f32_16x16x32_bf16 v[70:73], v[142:145], v[188:191], v[70:73]
	v_mfma_f32_16x16x32_bf16 v[74:77], v[134:137], v[188:191], v[74:77]
	v_mfma_f32_16x16x32_bf16 v[66:69], v[134:137], v[196:199], v[66:69]
	v_mfma_f32_16x16x32_bf16 v[62:65], v[142:145], v[196:199], v[62:65]
	v_mfma_f32_16x16x32_bf16 v[54:57], v[142:145], v[204:207], v[54:57]
	v_mfma_f32_16x16x32_bf16 v[58:61], v[134:137], v[204:207], v[58:61]
	v_mfma_f32_16x16x32_bf16 v[82:85], v[138:141], v[184:187], v[82:85]
	v_mfma_f32_16x16x32_bf16 v[78:81], v[146:149], v[184:187], v[78:81]
	v_mfma_f32_16x16x32_bf16 v[70:73], v[146:149], v[192:195], v[70:73]
	v_mfma_f32_16x16x32_bf16 v[74:77], v[138:141], v[192:195], v[74:77]
	v_mfma_f32_16x16x32_bf16 v[66:69], v[138:141], v[200:203], v[66:69]
	v_mfma_f32_16x16x32_bf16 v[62:65], v[146:149], v[200:203], v[62:65]
	v_mfma_f32_16x16x32_bf16 v[54:57], v[146:149], v[208:211], v[54:57]
	v_mfma_f32_16x16x32_bf16 v[58:61], v[138:141], v[208:211], v[58:61]
	s_setprio 0
	s_setprio 1
	v_mfma_f32_16x16x32_bf16 v[50:53], v[150:153], v[180:183], v[50:53]
	v_mfma_f32_16x16x32_bf16 v[46:49], v[158:161], v[180:183], v[46:49]
	v_mfma_f32_16x16x32_bf16 v[38:41], v[158:161], v[188:191], v[38:41]
	v_mfma_f32_16x16x32_bf16 v[42:45], v[150:153], v[188:191], v[42:45]
	v_mfma_f32_16x16x32_bf16 v[34:37], v[150:153], v[196:199], v[34:37]
	v_mfma_f32_16x16x32_bf16 v[28:31], v[158:161], v[196:199], v[28:31]
	v_mfma_f32_16x16x32_bf16 v[20:23], v[158:161], v[204:207], v[20:23]
	v_mfma_f32_16x16x32_bf16 v[24:27], v[150:153], v[204:207], v[24:27]
	v_mfma_f32_16x16x32_bf16 v[50:53], v[154:157], v[184:187], v[50:53]
	v_mfma_f32_16x16x32_bf16 v[46:49], v[172:175], v[184:187], v[46:49]
	v_mfma_f32_16x16x32_bf16 v[38:41], v[172:175], v[192:195], v[38:41]
	v_mfma_f32_16x16x32_bf16 v[42:45], v[154:157], v[192:195], v[42:45]
	v_mfma_f32_16x16x32_bf16 v[34:37], v[154:157], v[200:203], v[34:37]
	v_mfma_f32_16x16x32_bf16 v[28:31], v[172:175], v[200:203], v[28:31]
	v_mfma_f32_16x16x32_bf16 v[20:23], v[172:175], v[208:211], v[20:23]
	v_mfma_f32_16x16x32_bf16 v[24:27], v[154:157], v[208:211], v[24:27]
	s_setprio 0
	s_barrier
	s_add_i32 s54, s56, s13
	v_lshl_add_u64 v[212:213], s[38:39], 0, v[32:33]
	s_mov_b32 m0, s54
	ds_read_b128 v[180:183], v179 offset:16384
	ds_read_b128 v[184:187], v179 offset:17408
	ds_read_b128 v[188:191], v179 offset:18432
	ds_read_b128 v[192:195], v179 offset:19456
	ds_read_b128 v[196:199], v179 offset:20480
	ds_read_b128 v[200:203], v179 offset:21504
	ds_read_b128 v[204:207], v179 offset:22528
	ds_read_b128 v[208:211], v179 offset:23552
	global_load_lds_dwordx4 v[212:213], off
	s_add_i32 m0, s54, 0x2000
	s_add_u32 s54, s38, 0x80000
	v_lshl_add_u64 v[214:215], s[38:39], 0, v[166:167]
	s_addc_u32 s55, s39, 0
	s_add_i32 s56, s57, s13
	global_load_lds_dwordx4 v[214:215], off
	v_lshl_add_u64 v[216:217], s[54:55], 0, v[32:33]
	s_mov_b32 m0, s56
	v_lshl_add_u64 v[220:221], s[40:41], 0, v[164:165]
	global_load_lds_dwordx4 v[216:217], off
	v_lshl_add_u64 v[216:217], s[54:55], 0, v[166:167]
	s_add_i32 m0, s56, 0x2000
	s_nop 0
	global_load_lds_dwordx4 v[216:217], off
	v_lshl_add_u64 v[216:217], s[40:41], 0, v[162:163]
	s_mov_b32 m0, s24
	s_nop 0
	global_load_lds_dwordx4 v[216:217], off
	s_mov_b32 m0, s25
	s_nop 0
	global_load_lds_dwordx4 v[220:221], off
	s_waitcnt vmcnt(8)
	s_waitcnt lgkmcnt(0)
	s_barrier
	s_setprio 1
	s_waitcnt lgkmcnt(0)
	v_mfma_f32_16x16x32_bf16 v[16:19], v[134:137], v[180:183], v[16:19]
	v_mfma_f32_16x16x32_bf16 v[12:15], v[142:145], v[180:183], v[12:15]
	v_mfma_f32_16x16x32_bf16 v[4:7], v[142:145], v[188:191], v[4:7]
	v_mfma_f32_16x16x32_bf16 v[8:11], v[134:137], v[188:191], v[8:11]
	v_mfma_f32_16x16x32_bf16 v[0:3], v[134:137], v[196:199], v[0:3]
	v_mfma_f32_16x16x32_bf16 v[86:89], v[142:145], v[196:199], v[86:89]
	v_mfma_f32_16x16x32_bf16 v[94:97], v[142:145], v[204:207], v[94:97]
	v_mfma_f32_16x16x32_bf16 v[90:93], v[134:137], v[204:207], v[90:93]
	v_mfma_f32_16x16x32_bf16 v[16:19], v[138:141], v[184:187], v[16:19]
	v_mfma_f32_16x16x32_bf16 v[12:15], v[146:149], v[184:187], v[12:15]
	v_mfma_f32_16x16x32_bf16 v[4:7], v[146:149], v[192:195], v[4:7]
	v_mfma_f32_16x16x32_bf16 v[8:11], v[138:141], v[192:195], v[8:11]
	v_mfma_f32_16x16x32_bf16 v[0:3], v[138:141], v[200:203], v[0:3]
	v_mfma_f32_16x16x32_bf16 v[86:89], v[146:149], v[200:203], v[86:89]
	v_mfma_f32_16x16x32_bf16 v[94:97], v[146:149], v[208:211], v[94:97]
	v_mfma_f32_16x16x32_bf16 v[90:93], v[138:141], v[208:211], v[90:93]
	s_setprio 0
	s_setprio 1
	v_mfma_f32_16x16x32_bf16 v[98:101], v[150:153], v[180:183], v[98:101]
	v_mfma_f32_16x16x32_bf16 v[102:105], v[158:161], v[180:183], v[102:105]
	v_mfma_f32_16x16x32_bf16 v[110:113], v[158:161], v[188:191], v[110:113]
	v_mfma_f32_16x16x32_bf16 v[106:109], v[150:153], v[188:191], v[106:109]
	v_mfma_f32_16x16x32_bf16 v[114:117], v[150:153], v[196:199], v[114:117]
	v_mfma_f32_16x16x32_bf16 v[118:121], v[158:161], v[196:199], v[118:121]
	v_mfma_f32_16x16x32_bf16 v[126:129], v[158:161], v[204:207], v[126:129]
	v_mfma_f32_16x16x32_bf16 v[122:125], v[150:153], v[204:207], v[122:125]
	v_mfma_f32_16x16x32_bf16 v[98:101], v[154:157], v[184:187], v[98:101]
	v_mfma_f32_16x16x32_bf16 v[102:105], v[172:175], v[184:187], v[102:105]
	v_mfma_f32_16x16x32_bf16 v[110:113], v[172:175], v[192:195], v[110:113]
	v_mfma_f32_16x16x32_bf16 v[106:109], v[154:157], v[192:195], v[106:109]
	v_mfma_f32_16x16x32_bf16 v[114:117], v[154:157], v[200:203], v[114:117]
	v_mfma_f32_16x16x32_bf16 v[118:121], v[172:175], v[200:203], v[118:121]
	v_mfma_f32_16x16x32_bf16 v[126:129], v[172:175], v[208:211], v[126:129]
	v_mfma_f32_16x16x32_bf16 v[122:125], v[154:157], v[208:211], v[122:125]
	s_setprio 0
	s_barrier
	s_add_i32 s54, 0, 0x18000
	s_add_i32 s55, 0, 0x1c000
	v_add_u32_e32 v146, s54, v178
	v_add_u32_e32 v172, s55, v178
	ds_read_b128 v[134:137], v146
	ds_read_b128 v[138:141], v146 offset:1024
	ds_read_b128 v[142:145], v146 offset:2048
	ds_read_b128 v[146:149], v146 offset:3072
	ds_read_b128 v[150:153], v172
	ds_read_b128 v[154:157], v172 offset:1024
	ds_read_b128 v[158:161], v172 offset:2048
	ds_read_b128 v[172:175], v172 offset:3072
	s_add_u32 s40, s40, 0x80000
	s_addc_u32 s41, s41, 0
	s_mov_b32 m0, s33
	v_lshl_add_u64 v[222:223], s[40:41], 0, v[162:163]
	ds_read_b128 v[180:183], v179 offset:32768
	ds_read_b128 v[184:187], v179 offset:33792
	ds_read_b128 v[188:191], v179 offset:34816
	ds_read_b128 v[192:195], v179 offset:35840
	ds_read_b128 v[196:199], v179 offset:36864
	ds_read_b128 v[200:203], v179 offset:37888
	ds_read_b128 v[204:207], v179 offset:38912
	ds_read_b128 v[208:211], v179 offset:39936
	global_load_lds_dwordx4 v[222:223], off
	v_lshl_add_u64 v[222:223], s[40:41], 0, v[164:165]
	s_mov_b32 m0, s36
	s_nop 0
	global_load_lds_dwordx4 v[222:223], off
	s_waitcnt vmcnt(8)
	s_waitcnt lgkmcnt(0)
	s_barrier
	s_setprio 1
	s_waitcnt lgkmcnt(0)
	v_mfma_f32_16x16x32_bf16 v[82:85], v[134:137], v[180:183], v[82:85]
	v_mfma_f32_16x16x32_bf16 v[78:81], v[142:145], v[180:183], v[78:81]
	v_mfma_f32_16x16x32_bf16 v[70:73], v[142:145], v[188:191], v[70:73]
	v_mfma_f32_16x16x32_bf16 v[74:77], v[134:137], v[188:191], v[74:77]
	v_mfma_f32_16x16x32_bf16 v[66:69], v[134:137], v[196:199], v[66:69]
	v_mfma_f32_16x16x32_bf16 v[62:65], v[142:145], v[196:199], v[62:65]
	v_mfma_f32_16x16x32_bf16 v[54:57], v[142:145], v[204:207], v[54:57]
	v_mfma_f32_16x16x32_bf16 v[58:61], v[134:137], v[204:207], v[58:61]
	v_mfma_f32_16x16x32_bf16 v[82:85], v[138:141], v[184:187], v[82:85]
	v_mfma_f32_16x16x32_bf16 v[78:81], v[146:149], v[184:187], v[78:81]
	v_mfma_f32_16x16x32_bf16 v[70:73], v[146:149], v[192:195], v[70:73]
	v_mfma_f32_16x16x32_bf16 v[74:77], v[138:141], v[192:195], v[74:77]
	v_mfma_f32_16x16x32_bf16 v[66:69], v[138:141], v[200:203], v[66:69]
	v_mfma_f32_16x16x32_bf16 v[62:65], v[146:149], v[200:203], v[62:65]
	v_mfma_f32_16x16x32_bf16 v[54:57], v[146:149], v[208:211], v[54:57]
	v_mfma_f32_16x16x32_bf16 v[58:61], v[138:141], v[208:211], v[58:61]
	s_setprio 0
	s_setprio 1
	v_mfma_f32_16x16x32_bf16 v[50:53], v[150:153], v[180:183], v[50:53]
	v_mfma_f32_16x16x32_bf16 v[46:49], v[158:161], v[180:183], v[46:49]
	v_mfma_f32_16x16x32_bf16 v[38:41], v[158:161], v[188:191], v[38:41]
	v_mfma_f32_16x16x32_bf16 v[42:45], v[150:153], v[188:191], v[42:45]
	v_mfma_f32_16x16x32_bf16 v[34:37], v[150:153], v[196:199], v[34:37]
	v_mfma_f32_16x16x32_bf16 v[28:31], v[158:161], v[196:199], v[28:31]
	v_mfma_f32_16x16x32_bf16 v[20:23], v[158:161], v[204:207], v[20:23]
	v_mfma_f32_16x16x32_bf16 v[24:27], v[150:153], v[204:207], v[24:27]
	v_mfma_f32_16x16x32_bf16 v[50:53], v[154:157], v[184:187], v[50:53]
	v_mfma_f32_16x16x32_bf16 v[46:49], v[172:175], v[184:187], v[46:49]
	v_mfma_f32_16x16x32_bf16 v[38:41], v[172:175], v[192:195], v[38:41]
	v_mfma_f32_16x16x32_bf16 v[42:45], v[154:157], v[192:195], v[42:45]
	v_mfma_f32_16x16x32_bf16 v[34:37], v[154:157], v[200:203], v[34:37]
	v_mfma_f32_16x16x32_bf16 v[28:31], v[172:175], v[200:203], v[28:31]
	v_mfma_f32_16x16x32_bf16 v[20:23], v[172:175], v[208:211], v[20:23]
	v_mfma_f32_16x16x32_bf16 v[24:27], v[154:157], v[208:211], v[24:27]
	s_setprio 0
	s_barrier
	s_add_i32 s40, s54, s13
	v_lshl_add_u64 v[212:213], v[212:213], 0, s[34:35]
	s_mov_b32 m0, s40
	ds_read_b128 v[180:183], v179 offset:49152
	ds_read_b128 v[184:187], v179 offset:50176
	ds_read_b128 v[188:191], v179 offset:51200
	ds_read_b128 v[192:195], v179 offset:52224
	ds_read_b128 v[196:199], v179 offset:53248
	ds_read_b128 v[200:203], v179 offset:54272
	ds_read_b128 v[204:207], v179 offset:55296
	ds_read_b128 v[208:211], v179 offset:56320
	global_load_lds_dwordx4 v[212:213], off
	s_add_i32 m0, s40, 0x2000
	s_add_u32 s38, s38, 0x80080
	v_lshl_add_u64 v[212:213], v[214:215], 0, s[34:35]
	s_addc_u32 s39, s39, 0
	s_add_i32 s40, s55, s13
	global_load_lds_dwordx4 v[212:213], off
	v_lshl_add_u64 v[212:213], s[38:39], 0, v[32:33]
	s_mov_b32 m0, s40
	s_nop 0
	global_load_lds_dwordx4 v[212:213], off
	v_lshl_add_u64 v[212:213], s[38:39], 0, v[166:167]
	s_add_i32 m0, s40, 0x2000
	s_nop 0
	global_load_lds_dwordx4 v[212:213], off
	v_lshl_add_u64 v[212:213], v[216:217], 0, s[34:35]
	s_mov_b32 m0, s43
	s_nop 0
	global_load_lds_dwordx4 v[212:213], off
	v_lshl_add_u64 v[212:213], v[220:221], 0, s[34:35]
	s_mov_b32 m0, s44
	s_nop 0
	global_load_lds_dwordx4 v[212:213], off
	s_waitcnt vmcnt(8)
	s_waitcnt lgkmcnt(0)
	s_barrier
	s_setprio 1
	s_waitcnt lgkmcnt(0)
	v_mfma_f32_16x16x32_bf16 v[16:19], v[134:137], v[180:183], v[16:19]
	v_mfma_f32_16x16x32_bf16 v[12:15], v[142:145], v[180:183], v[12:15]
	v_mfma_f32_16x16x32_bf16 v[4:7], v[142:145], v[188:191], v[4:7]
	v_mfma_f32_16x16x32_bf16 v[8:11], v[134:137], v[188:191], v[8:11]
	v_mfma_f32_16x16x32_bf16 v[0:3], v[134:137], v[196:199], v[0:3]
	v_mfma_f32_16x16x32_bf16 v[86:89], v[142:145], v[196:199], v[86:89]
	v_mfma_f32_16x16x32_bf16 v[94:97], v[142:145], v[204:207], v[94:97]
	v_mfma_f32_16x16x32_bf16 v[90:93], v[134:137], v[204:207], v[90:93]
	v_mfma_f32_16x16x32_bf16 v[16:19], v[138:141], v[184:187], v[16:19]
	v_mfma_f32_16x16x32_bf16 v[12:15], v[146:149], v[184:187], v[12:15]
	v_mfma_f32_16x16x32_bf16 v[4:7], v[146:149], v[192:195], v[4:7]
	v_mfma_f32_16x16x32_bf16 v[8:11], v[138:141], v[192:195], v[8:11]
	v_mfma_f32_16x16x32_bf16 v[0:3], v[138:141], v[200:203], v[0:3]
	v_mfma_f32_16x16x32_bf16 v[86:89], v[146:149], v[200:203], v[86:89]
	v_mfma_f32_16x16x32_bf16 v[94:97], v[146:149], v[208:211], v[94:97]
	v_mfma_f32_16x16x32_bf16 v[90:93], v[138:141], v[208:211], v[90:93]
	s_setprio 0
	s_setprio 1
	v_mfma_f32_16x16x32_bf16 v[98:101], v[150:153], v[180:183], v[98:101]
	v_mfma_f32_16x16x32_bf16 v[102:105], v[158:161], v[180:183], v[102:105]
	v_mfma_f32_16x16x32_bf16 v[110:113], v[158:161], v[188:191], v[110:113]
	v_mfma_f32_16x16x32_bf16 v[106:109], v[150:153], v[188:191], v[106:109]
	v_mfma_f32_16x16x32_bf16 v[114:117], v[150:153], v[196:199], v[114:117]
	v_mfma_f32_16x16x32_bf16 v[118:121], v[158:161], v[196:199], v[118:121]
	v_mfma_f32_16x16x32_bf16 v[126:129], v[158:161], v[204:207], v[126:129]
	v_mfma_f32_16x16x32_bf16 v[122:125], v[150:153], v[204:207], v[122:125]
	v_mfma_f32_16x16x32_bf16 v[98:101], v[154:157], v[184:187], v[98:101]
	v_mfma_f32_16x16x32_bf16 v[102:105], v[172:175], v[184:187], v[102:105]
	v_mfma_f32_16x16x32_bf16 v[110:113], v[172:175], v[192:195], v[110:113]
	v_mfma_f32_16x16x32_bf16 v[106:109], v[154:157], v[192:195], v[106:109]
	v_mfma_f32_16x16x32_bf16 v[114:117], v[154:157], v[200:203], v[114:117]
	v_mfma_f32_16x16x32_bf16 v[118:121], v[172:175], v[200:203], v[118:121]
	v_mfma_f32_16x16x32_bf16 v[126:129], v[172:175], v[208:211], v[126:129]
	v_mfma_f32_16x16x32_bf16 v[122:125], v[154:157], v[208:211], v[122:125]
	s_setprio 0
	s_barrier
	s_add_i32 s53, s53, 2
	s_add_u32 s30, s30, 0x100
	s_addc_u32 s31, s31, 0
	s_cmp_gt_u32 s53, 29
	s_cbranch_scc0 .LBB0_888
	s_and_b64 vcc, exec, s[18:19]
	s_cbranch_vccz .LBB0_891
	s_barrier
